# grid barrier: the acquire-side L1 invalidate issued when the arrival ticket is read, so its latency runs under the wait for the other workgroups
# speedup vs baseline: 1.0091x; 1.0091x over previous
; DI unsigned xb_ld(unsigned* q) { return __hip_atomic_load(q, __ATOMIC_RELAXED, __HIP_MEMORY_SCOPE_AGENT); }
; DI unsigned xb_add(unsigned* q, unsigned v) { return __hip_atomic_fetch_add(q, v, __ATOMIC_RELAXED, __HIP_MEMORY_SCOPE_AGENT); }
; #define XB_SPIN(cond, bar) do { unsigned _sp = 0; while (cond) { __builtin_amdgcn_s_sleep(1); \
;     if ((++_sp & 255u) == 0u) { if (xb_ld(&(bar)[XB_TMO])) break; if (_sp > XB_SPIN_CAP) { atomicAdd(&(bar)[XB_TMO], 1u); break; } } } } while (0)
; DI void grid_bar(unsigned* bar, volatile LAS unsigned* st, int wid) {
;     ...
;             const unsigned old = xb_add(&bar[XB_XSUB(x)], 1u);
;             const unsigned gen = old / nloc;
;             if (old + 1u == (gen + 1u) * nloc) {
;                 __builtin_amdgcn_fence(__ATOMIC_RELEASE, "agent");
;                 asm volatile("s_waitcnt vmcnt(0)" ::: "memory");
;                 const unsigned og = xb_add(&bar[XB_TOP], 1u);
;                 const unsigned tg = og / nx;
;                 if (og + 1u == (tg + 1u) * nx) xb_add(&bar[XB_TOPGEN], 1u);
;                 else XB_SPIN(xb_ld(&bar[XB_TOPGEN]) == tg, bar);
;                 __builtin_amdgcn_fence(__ATOMIC_ACQUIRE, "agent");
;                 xb_add(&bar[XB_XGEN(x)], 1u);
;                 asm volatile("s_waitcnt vmcnt(0)" ::: "memory");
;             } else {
;                 XB_SPIN(xb_ld(&bar[XB_XGEN(x)]) == gen, bar);
.LBB0_261:
	s_or_b64 exec, exec, s[14:15]
	v_cvt_f32_u32_e32 v4, v2
	s_waitcnt vmcnt(0)
	v_readfirstlane_b32 s12, v3
	buffer_inv sc1
	v_sub_u32_e32 v3, 0, v2
	v_rcp_iflag_f32_e32 v4, v4
	v_add_u32_e32 v5, s12, v1
	v_mul_f32_e32 v4, 0x4f7ffffe, v4
	v_cvt_u32_f32_e32 v4, v4
	v_mul_lo_u32 v1, v3, v4
	v_mul_hi_u32 v1, v4, v1
	v_add_u32_e32 v1, v4, v1
	v_mul_hi_u32 v1, v5, v1
	v_mul_lo_u32 v3, v1, v2
	v_sub_u32_e32 v3, v5, v3
	v_add_u32_e32 v4, 1, v1
	v_cmp_ge_u32_e32 vcc, v3, v2
	s_nop 1
	v_cndmask_b32_e32 v1, v1, v4, vcc
	v_sub_u32_e32 v4, v3, v2
	v_cndmask_b32_e32 v3, v3, v4, vcc
	v_add_u32_e32 v4, 1, v1
	v_cmp_ge_u32_e32 vcc, v3, v2
	v_add_u32_e32 v3, 1, v5
	s_nop 0
	v_cndmask_b32_e32 v1, v1, v4, vcc
	v_mul_lo_u32 v4, v2, v1
	v_add_u32_e32 v2, v4, v2
	v_cmp_ne_u32_e32 vcc, v3, v2
	s_and_saveexec_b64 s[12:13], vcc
	s_xor_b64 s[12:13], exec, s[12:13]
	s_cbranch_execz .LBB0_275
	s_waitcnt lgkmcnt(0)
	v_mov_b32_e32 v0, 0x2000
	global_load_dword v0, v0, s[10:11] offset:1024 sc1
	s_add_u32 s18, s10, 0x2400
	s_addc_u32 s19, s11, 0
	s_waitcnt vmcnt(0)
	v_cmp_eq_u32_e32 vcc, v0, v1
	s_and_saveexec_b64 s[14:15], vcc
	s_cbranch_execz .LBB0_274
	s_add_u32 s16, s8, 0xcd80200
	s_addc_u32 s17, s9, 0
	s_mov_b32 s30, 1
	s_mov_b64 s[20:21], 0
	v_mov_b32_e32 v0, 0
	s_branch .LBB0_265

; DI unsigned xb_ld(unsigned* q) { return __hip_atomic_load(q, __ATOMIC_RELAXED, __HIP_MEMORY_SCOPE_AGENT); }
; #define XB_SPIN(cond, bar) do { unsigned _sp = 0; while (cond) { __builtin_amdgcn_s_sleep(1); \
;     if ((++_sp & 255u) == 0u) { if (xb_ld(&(bar)[XB_TMO])) break; if (_sp > XB_SPIN_CAP) { atomicAdd(&(bar)[XB_TMO], 1u); break; } } } } while (0)
; DI void grid_bar(unsigned* bar, volatile LAS unsigned* st, int wid) {
;     ...
;                 XB_SPIN(xb_ld(&bar[XB_XGEN(x)]) == gen, bar);
;                 __builtin_amdgcn_fence(__ATOMIC_ACQUIRE, "agent");
;                 asm volatile("s_waitcnt vmcnt(0)" ::: "memory");
.LBB0_274:
	s_or_b64 exec, exec, s[14:15]
	s_waitcnt vmcnt(0)
	s_waitcnt vmcnt(0)

; DI unsigned xb_add(unsigned* q, unsigned v) { return __hip_atomic_fetch_add(q, v, __ATOMIC_RELAXED, __HIP_MEMORY_SCOPE_AGENT); }
; DI void grid_bar(unsigned* bar, volatile LAS unsigned* st, int wid) {
;     ...
;                 __builtin_amdgcn_fence(__ATOMIC_ACQUIRE, "agent");
;                 xb_add(&bar[XB_XGEN(x)], 1u);
;                 asm volatile("s_waitcnt vmcnt(0)" ::: "memory");
.LBB0_292:
	s_or_b64 exec, exec, s[8:9]
	s_mov_b64 s[8:9], exec
	v_mbcnt_lo_u32_b32 v0, s8, 0
	v_mbcnt_hi_u32_b32 v0, s9, v0
	v_cmp_eq_u32_e32 vcc, 0, v0
	s_waitcnt vmcnt(0)
	s_and_saveexec_b64 s[12:13], vcc
	s_cbranch_execz .LBB0_294
	s_bcnt1_i32_b64 s8, s[8:9]
	v_mov_b32_e32 v0, 0x2000
	v_mov_b32_e32 v1, s8
	global_atomic_add v0, v1, s[10:11] offset:1024
